# v15+once + hand-written P4 weight conversions: both tiles' loads issued up front per wave
# speedup vs baseline: 1.0008x; 1.0008x over previous
; #define LAS __attribute__((address_space(3)))
; __device__ __forceinline__ void p0_transpose_kn(const float* W, int K, int N, bf16_t* WT, int row_off, LAS float* scr, int kb, int nb, int lane) {
;     const int k0 = 64 * kb, n0 = 32 * nb;
;     float wv[32];
; #pragma unroll
;     for (int i = 0; i < 32; ++i) wv[i] = W[(size_t)(k0 + 2 * i + (lane >> 5)) * N + n0 + (lane & 31)];
; __global__ void __launch_bounds__(512, 2) mk_fwd(Args args) {
;     ...
;             for (int it = gw; it < 16 * 128 + 3 * 512; it += NGW) {
;                 int r = it;
;                 if (r < 16 * 128) { const int kb = r / 128, j = r % 128, sg = j >> 5, seg = sg == 0 ? 3 : sg + 6; p0_transpose_kn(w_in, 1024, 10240, Wt_in, 0, scr, kb, seg * 32 + (j & 31), lane); continue; } r -= 16 * 128;
;                 if (r < 512) { p0_transpose_kn(w_sb, 1024, 1024, Wt_sbhg, 0, scr, r / 32, r % 32, lane); continue; } r -= 512;
;                 if (r < 512) { p0_transpose_kn(w_hg, 1024, 1024, Wt_sbhg, 1024, scr, r / 32, r % 32, lane); continue; } r -= 512;
;                 p0_transpose_kn(w_out, 1024, 1024, Wt_out, 0, scr, r / 32, r % 32, lane);
.LBB0_399:
	s_cmp_lt_i32 s68, 5
	s_cselect_b64 s[6:7], -1, 0
	s_add_u32 s30, s66, 0x1500000
	s_addc_u32 s31, s67, 0
	s_add_u32 s28, s66, 0x1900000
	s_addc_u32 s29, s67, 0
	s_and_b64 s[34:35], s[6:7], s[4:5]
	s_andn2_b64 vcc, exec, s[34:35]
	s_cbranch_vccnz .LBB0_451
	v_readlane_b32 s46, v250, 17
	v_readlane_b32 s47, v250, 18
	v_readfirstlane_b32 s4, v169
	v_readfirstlane_b32 s5, v168
	s_movk_i32 s22, 0x7fff
	s_mov_b32 s23, 0xffff0000
	v_lshrrev_b32_e32 v69, 5, v170
	v_and_b32_e32 v70, 31, v170
	v_mul_u32_u24_e32 v71, 0x2800, v69
	v_add_lshl_u32 v64, v71, v70, 2
	v_lshlrev_b32_e32 v71, 10, v69
	v_add_lshl_u32 v65, v71, v70, 2
	v_mul_u32_u24_e32 v71, 33, v69
	v_add_lshl_u32 v71, v71, v70, 2
	v_lshl_add_u32 v67, v168, 14, v71
	v_lshrrev_b32_e32 v72, 3, v170
	v_and_b32_e32 v73, 7, v170
	v_lshlrev_b32_e32 v74, 11, v72
	v_lshl_add_u32 v66, v73, 4, v74
	v_mul_u32_u24_e32 v75, 0x108, v73
	v_add_lshl_u32 v75, v75, v72, 2
	v_lshl_add_u32 v68, v168, 14, v75
	v_readlane_b32 s6, v250, 5
	v_readlane_b32 s7, v250, 6
	s_lshr_b32 s8, s4, 7
	s_and_b32 s9, s4, 127
	s_lshr_b32 s10, s9, 5
	s_and_b32 s9, s9, 31
	s_add_u32 s11, s10, 6
	s_cmp_eq_u32 s10, 0
	s_cselect_b32 s10, 3, s11
	s_lshl_b32 s10, s10, 5
	s_add_u32 s10, s10, s9
	s_mul_i32 s9, s8, 0x280000
	s_lshl_b32 s11, s10, 7
	s_add_u32 s9, s9, s11
	s_add_u32 s12, s6, s9
	s_addc_u32 s13, s7, 0
	s_lshl_b32 s9, s10, 16
	s_lshl_b32 s11, s8, 7
	s_add_u32 s9, s9, s11
	s_add_u32 s14, s74, s9
	s_addc_u32 s15, s75, 0
	global_load_dword v0, v64, s[12:13]
	s_add_u32 s12, s12, 0x14000
	s_addc_u32 s13, s13, 0
	global_load_dword v1, v64, s[12:13]
	s_add_u32 s12, s12, 0x14000
	s_addc_u32 s13, s13, 0
	global_load_dword v2, v64, s[12:13]
	s_add_u32 s12, s12, 0x14000
	s_addc_u32 s13, s13, 0
	global_load_dword v3, v64, s[12:13]
	s_add_u32 s12, s12, 0x14000
	s_addc_u32 s13, s13, 0
	global_load_dword v4, v64, s[12:13]
	s_add_u32 s12, s12, 0x14000
	s_addc_u32 s13, s13, 0
	global_load_dword v5, v64, s[12:13]
	s_add_u32 s12, s12, 0x14000
	s_addc_u32 s13, s13, 0
	global_load_dword v6, v64, s[12:13]
	s_add_u32 s12, s12, 0x14000
	s_addc_u32 s13, s13, 0
	global_load_dword v7, v64, s[12:13]
	s_add_u32 s12, s12, 0x14000
	s_addc_u32 s13, s13, 0
	global_load_dword v8, v64, s[12:13]
	s_add_u32 s12, s12, 0x14000
	s_addc_u32 s13, s13, 0
	global_load_dword v9, v64, s[12:13]
	s_add_u32 s12, s12, 0x14000
	s_addc_u32 s13, s13, 0
	global_load_dword v10, v64, s[12:13]
	s_add_u32 s12, s12, 0x14000
	s_addc_u32 s13, s13, 0
	global_load_dword v11, v64, s[12:13]
	s_add_u32 s12, s12, 0x14000
	s_addc_u32 s13, s13, 0
	global_load_dword v12, v64, s[12:13]
	s_add_u32 s12, s12, 0x14000
	s_addc_u32 s13, s13, 0
	global_load_dword v13, v64, s[12:13]
	s_add_u32 s12, s12, 0x14000
	s_addc_u32 s13, s13, 0
	global_load_dword v14, v64, s[12:13]
	s_add_u32 s12, s12, 0x14000
	s_addc_u32 s13, s13, 0
	global_load_dword v15, v64, s[12:13]
	s_add_u32 s12, s12, 0x14000
	s_addc_u32 s13, s13, 0
	global_load_dword v16, v64, s[12:13]
	s_add_u32 s12, s12, 0x14000
	s_addc_u32 s13, s13, 0
	global_load_dword v17, v64, s[12:13]
	s_add_u32 s12, s12, 0x14000
	s_addc_u32 s13, s13, 0
	global_load_dword v18, v64, s[12:13]
	s_add_u32 s12, s12, 0x14000
	s_addc_u32 s13, s13, 0
	global_load_dword v19, v64, s[12:13]
	s_add_u32 s12, s12, 0x14000
	s_addc_u32 s13, s13, 0
	global_load_dword v20, v64, s[12:13]
	s_add_u32 s12, s12, 0x14000
	s_addc_u32 s13, s13, 0
	global_load_dword v21, v64, s[12:13]
	s_add_u32 s12, s12, 0x14000
	s_addc_u32 s13, s13, 0
	global_load_dword v22, v64, s[12:13]
	s_add_u32 s12, s12, 0x14000
	s_addc_u32 s13, s13, 0
	global_load_dword v23, v64, s[12:13]
	s_add_u32 s12, s12, 0x14000
	s_addc_u32 s13, s13, 0
	global_load_dword v24, v64, s[12:13]
	s_add_u32 s12, s12, 0x14000
	s_addc_u32 s13, s13, 0
	global_load_dword v25, v64, s[12:13]
	s_add_u32 s12, s12, 0x14000
	s_addc_u32 s13, s13, 0
	global_load_dword v26, v64, s[12:13]
	s_add_u32 s12, s12, 0x14000
	s_addc_u32 s13, s13, 0
	global_load_dword v27, v64, s[12:13]
	s_add_u32 s12, s12, 0x14000
	s_addc_u32 s13, s13, 0
	global_load_dword v28, v64, s[12:13]
	s_add_u32 s12, s12, 0x14000
	s_addc_u32 s13, s13, 0
	global_load_dword v29, v64, s[12:13]
	s_add_u32 s12, s12, 0x14000
	s_addc_u32 s13, s13, 0
	global_load_dword v30, v64, s[12:13]
	s_add_u32 s12, s12, 0x14000
	s_addc_u32 s13, s13, 0
	global_load_dword v31, v64, s[12:13]
	s_cmpk_gt_u32 s4, 0x5ff
	s_cbranch_scc1 .Lp4_one
	s_lshr_b32 s8, s4, 9
	s_and_b32 s9, s4, 511
	s_lshr_b32 s10, s9, 5
	s_and_b32 s9, s9, 31
	v_readlane_b32 s6, v250, 13
	v_readlane_b32 s7, v250, 14
	s_mov_b64 s[16:17], s[30:31]
	s_cmp_eq_u32 s8, 0
	s_cbranch_scc1 .Lp4_k
	v_readlane_b32 s6, v250, 15
	v_readlane_b32 s7, v250, 16
	s_add_u32 s16, s30, 0x200000
	s_addc_u32 s17, s31, 0
	s_cmp_eq_u32 s8, 1
	s_cbranch_scc1 .Lp4_k
	s_mov_b64 s[6:7], s[60:61]
	s_mov_b64 s[16:17], s[28:29]
; #define LAS __attribute__((address_space(3)))
; __device__ __forceinline__ void p0_transpose_kn(const float* W, int K, int N, bf16_t* WT, int row_off, LAS float* scr, int kb, int nb, int lane) {
;     const int k0 = 64 * kb, n0 = 32 * nb;
;     float wv[32];
; #pragma unroll
;     for (int i = 0; i < 32; ++i) wv[i] = W[(size_t)(k0 + 2 * i + (lane >> 5)) * N + n0 + (lane & 31)];
; __global__ void __launch_bounds__(512, 2) mk_fwd(Args args) {
;     ...
;                 if (r < 512) { p0_transpose_kn(w_sb, 1024, 1024, Wt_sbhg, 0, scr, r / 32, r % 32, lane); continue; } r -= 512;
;                 if (r < 512) { p0_transpose_kn(w_hg, 1024, 1024, Wt_sbhg, 1024, scr, r / 32, r % 32, lane); continue; } r -= 512;
;                 p0_transpose_kn(w_out, 1024, 1024, Wt_out, 0, scr, r / 32, r % 32, lane);
.Lp4_k:
	s_lshl_b32 s11, s10, 18
	s_lshl_b32 s18, s9, 7
	s_add_u32 s11, s11, s18
	s_add_u32 s18, s6, s11
	s_addc_u32 s19, s7, 0
	s_lshl_b32 s11, s9, 16
	s_lshl_b32 s20, s10, 7
	s_add_u32 s11, s11, s20
	s_add_u32 s20, s16, s11
	s_addc_u32 s21, s17, 0
	global_load_dword v32, v65, s[18:19]
	s_add_u32 s18, s18, 0x2000
	s_addc_u32 s19, s19, 0
	global_load_dword v33, v65, s[18:19]
	s_add_u32 s18, s18, 0x2000
	s_addc_u32 s19, s19, 0
	global_load_dword v34, v65, s[18:19]
	s_add_u32 s18, s18, 0x2000
	s_addc_u32 s19, s19, 0
	global_load_dword v35, v65, s[18:19]
	s_add_u32 s18, s18, 0x2000
	s_addc_u32 s19, s19, 0
	global_load_dword v36, v65, s[18:19]
	s_add_u32 s18, s18, 0x2000
	s_addc_u32 s19, s19, 0
	global_load_dword v37, v65, s[18:19]
	s_add_u32 s18, s18, 0x2000
	s_addc_u32 s19, s19, 0
	global_load_dword v38, v65, s[18:19]
	s_add_u32 s18, s18, 0x2000
	s_addc_u32 s19, s19, 0
	global_load_dword v39, v65, s[18:19]
	s_add_u32 s18, s18, 0x2000
	s_addc_u32 s19, s19, 0
	global_load_dword v40, v65, s[18:19]
	s_add_u32 s18, s18, 0x2000
	s_addc_u32 s19, s19, 0
	global_load_dword v41, v65, s[18:19]
	s_add_u32 s18, s18, 0x2000
	s_addc_u32 s19, s19, 0
	global_load_dword v42, v65, s[18:19]
	s_add_u32 s18, s18, 0x2000
	s_addc_u32 s19, s19, 0
	global_load_dword v43, v65, s[18:19]
	s_add_u32 s18, s18, 0x2000
	s_addc_u32 s19, s19, 0
	global_load_dword v44, v65, s[18:19]
	s_add_u32 s18, s18, 0x2000
	s_addc_u32 s19, s19, 0
	global_load_dword v45, v65, s[18:19]
	s_add_u32 s18, s18, 0x2000
	s_addc_u32 s19, s19, 0
	global_load_dword v46, v65, s[18:19]
	s_add_u32 s18, s18, 0x2000
	s_addc_u32 s19, s19, 0
	global_load_dword v47, v65, s[18:19]
	s_add_u32 s18, s18, 0x2000
	s_addc_u32 s19, s19, 0
	global_load_dword v48, v65, s[18:19]
	s_add_u32 s18, s18, 0x2000
	s_addc_u32 s19, s19, 0
	global_load_dword v49, v65, s[18:19]
	s_add_u32 s18, s18, 0x2000
	s_addc_u32 s19, s19, 0
	global_load_dword v50, v65, s[18:19]
	s_add_u32 s18, s18, 0x2000
	s_addc_u32 s19, s19, 0
	global_load_dword v51, v65, s[18:19]
	s_add_u32 s18, s18, 0x2000
	s_addc_u32 s19, s19, 0
	global_load_dword v52, v65, s[18:19]
	s_add_u32 s18, s18, 0x2000
	s_addc_u32 s19, s19, 0
	global_load_dword v53, v65, s[18:19]
	s_add_u32 s18, s18, 0x2000
	s_addc_u32 s19, s19, 0
	global_load_dword v54, v65, s[18:19]
	s_add_u32 s18, s18, 0x2000
	s_addc_u32 s19, s19, 0
	global_load_dword v55, v65, s[18:19]
	s_add_u32 s18, s18, 0x2000
	s_addc_u32 s19, s19, 0
	global_load_dword v56, v65, s[18:19]
	s_add_u32 s18, s18, 0x2000
	s_addc_u32 s19, s19, 0
	global_load_dword v57, v65, s[18:19]
	s_add_u32 s18, s18, 0x2000
	s_addc_u32 s19, s19, 0
	global_load_dword v58, v65, s[18:19]
	s_add_u32 s18, s18, 0x2000
	s_addc_u32 s19, s19, 0
	global_load_dword v59, v65, s[18:19]
	s_add_u32 s18, s18, 0x2000
	s_addc_u32 s19, s19, 0
	global_load_dword v60, v65, s[18:19]
	s_add_u32 s18, s18, 0x2000
	s_addc_u32 s19, s19, 0
	global_load_dword v61, v65, s[18:19]
	s_add_u32 s18, s18, 0x2000
	s_addc_u32 s19, s19, 0
	global_load_dword v62, v65, s[18:19]
	s_add_u32 s18, s18, 0x2000
	s_addc_u32 s19, s19, 0
	global_load_dword v63, v65, s[18:19]
	s_waitcnt vmcnt(32)
	s_branch .Lp4_t1

; #define LAS __attribute__((address_space(3)))
; __device__ __forceinline__ unsigned pk2(float lo, float hi) { return f2bf(lo) | (f2bf(hi) << 16); }
; __device__ __forceinline__ void p0_transpose_kn(const float* W, int K, int N, bf16_t* WT, int row_off, LAS float* scr, int kb, int nb, int lane) {
;     ...
;     for (int i = 0; i < 32; ++i) wv[i] = W[(size_t)(k0 + 2 * i + (lane >> 5)) * N + n0 + (lane & 31)];
; #pragma unroll
;     for (int i = 0; i < 32; ++i) scr[(2 * i + (lane >> 5)) * 33 + (lane & 31)] = wv[i];
;     asm volatile("s_waitcnt lgkmcnt(0)" ::: "memory");
;     const int c = lane & 7;
; #pragma unroll
;     for (int j = 0; j < 4; ++j) { const int n = (lane >> 3) + 8 * j; const LAS float* s = scr + (8 * c) * 33 + n;
;         u32x4 o; o.x = pk2(s[0 * 33], s[1 * 33]); o.y = pk2(s[2 * 33], s[3 * 33]); o.z = pk2(s[4 * 33], s[5 * 33]); o.w = pk2(s[6 * 33], s[7 * 33]);
;         *(u32x4*)(WT + (size_t)(row_off + n0 + n) * K + k0 + 8 * c) = o; }
;     asm volatile("s_waitcnt lgkmcnt(0)" ::: "memory");
.Lp4_t1:
	ds_write_b32 v67, v0
	ds_write_b32 v67, v1 offset:264
	ds_write_b32 v67, v2 offset:528
	ds_write_b32 v67, v3 offset:792
	ds_write_b32 v67, v4 offset:1056
	ds_write_b32 v67, v5 offset:1320
	ds_write_b32 v67, v6 offset:1584
	ds_write_b32 v67, v7 offset:1848
	ds_write_b32 v67, v8 offset:2112
	ds_write_b32 v67, v9 offset:2376
	ds_write_b32 v67, v10 offset:2640
	ds_write_b32 v67, v11 offset:2904
	ds_write_b32 v67, v12 offset:3168
	ds_write_b32 v67, v13 offset:3432
	ds_write_b32 v67, v14 offset:3696
	ds_write_b32 v67, v15 offset:3960
	ds_write_b32 v67, v16 offset:4224
	ds_write_b32 v67, v17 offset:4488
	ds_write_b32 v67, v18 offset:4752
	ds_write_b32 v67, v19 offset:5016
	ds_write_b32 v67, v20 offset:5280
	ds_write_b32 v67, v21 offset:5544
	ds_write_b32 v67, v22 offset:5808
	ds_write_b32 v67, v23 offset:6072
	ds_write_b32 v67, v24 offset:6336
	ds_write_b32 v67, v25 offset:6600
	ds_write_b32 v67, v26 offset:6864
	ds_write_b32 v67, v27 offset:7128
	ds_write_b32 v67, v28 offset:7392
	ds_write_b32 v67, v29 offset:7656
	ds_write_b32 v67, v30 offset:7920
	ds_write_b32 v67, v31 offset:8184
	s_waitcnt lgkmcnt(0)
	ds_read2_b32 v[0:1], v68 offset1:33
	ds_read2_b32 v[2:3], v68 offset0:66 offset1:99
	ds_read2_b32 v[4:5], v68 offset0:132 offset1:165
	ds_read2_b32 v[6:7], v68 offset0:198 offset1:231
	ds_read2_b32 v[8:9], v68 offset0:8 offset1:41
	ds_read2_b32 v[10:11], v68 offset0:74 offset1:107
	ds_read2_b32 v[12:13], v68 offset0:140 offset1:173
	ds_read2_b32 v[14:15], v68 offset0:206 offset1:239
	ds_read2_b32 v[16:17], v68 offset0:16 offset1:49
	ds_read2_b32 v[18:19], v68 offset0:82 offset1:115
	ds_read2_b32 v[20:21], v68 offset0:148 offset1:181
	ds_read2_b32 v[22:23], v68 offset0:214 offset1:247
	ds_read2_b32 v[24:25], v68 offset0:24 offset1:57
	ds_read2_b32 v[26:27], v68 offset0:90 offset1:123
	ds_read2_b32 v[28:29], v68 offset0:156 offset1:189
	ds_read2_b32 v[30:31], v68 offset0:222 offset1:255
	s_waitcnt lgkmcnt(0)
	v_bfe_u32 v69, v0, 16, 1
	v_bfe_u32 v70, v1, 16, 1
	v_bfe_u32 v71, v2, 16, 1
	v_bfe_u32 v72, v3, 16, 1
	v_bfe_u32 v73, v4, 16, 1
	v_bfe_u32 v74, v5, 16, 1
	v_bfe_u32 v75, v6, 16, 1
	v_bfe_u32 v76, v7, 16, 1
	v_add3_u32 v0, v0, v69, s22
	v_add3_u32 v1, v1, v70, s22
	v_add3_u32 v2, v2, v71, s22
	v_add3_u32 v3, v3, v72, s22
	v_add3_u32 v4, v4, v73, s22
	v_add3_u32 v5, v5, v74, s22
	v_add3_u32 v6, v6, v75, s22
	v_add3_u32 v7, v7, v76, s22
	v_bfe_u32 v69, v8, 16, 1
	v_bfe_u32 v70, v9, 16, 1
	v_bfe_u32 v71, v10, 16, 1
	v_bfe_u32 v72, v11, 16, 1
	v_bfe_u32 v73, v12, 16, 1
	v_bfe_u32 v74, v13, 16, 1
	v_bfe_u32 v75, v14, 16, 1
	v_bfe_u32 v76, v15, 16, 1
	v_add3_u32 v8, v8, v69, s22
	v_add3_u32 v9, v9, v70, s22
	v_add3_u32 v10, v10, v71, s22
	v_add3_u32 v11, v11, v72, s22
	v_add3_u32 v12, v12, v73, s22
	v_add3_u32 v13, v13, v74, s22
	v_add3_u32 v14, v14, v75, s22
	v_add3_u32 v15, v15, v76, s22
	v_bfe_u32 v69, v16, 16, 1
	v_bfe_u32 v70, v17, 16, 1
	v_bfe_u32 v71, v18, 16, 1
	v_bfe_u32 v72, v19, 16, 1
	v_bfe_u32 v73, v20, 16, 1
	v_bfe_u32 v74, v21, 16, 1
	v_bfe_u32 v75, v22, 16, 1
	v_bfe_u32 v76, v23, 16, 1
	v_add3_u32 v16, v16, v69, s22
	v_add3_u32 v17, v17, v70, s22
	v_add3_u32 v18, v18, v71, s22
	v_add3_u32 v19, v19, v72, s22
	v_add3_u32 v20, v20, v73, s22
	v_add3_u32 v21, v21, v74, s22
	v_add3_u32 v22, v22, v75, s22
	v_add3_u32 v23, v23, v76, s22
	v_bfe_u32 v69, v24, 16, 1
	v_bfe_u32 v70, v25, 16, 1
	v_bfe_u32 v71, v26, 16, 1
	v_bfe_u32 v72, v27, 16, 1
	v_bfe_u32 v73, v28, 16, 1
	v_bfe_u32 v74, v29, 16, 1
	v_bfe_u32 v75, v30, 16, 1
	v_bfe_u32 v76, v31, 16, 1
	v_add3_u32 v24, v24, v69, s22
	v_add3_u32 v25, v25, v70, s22
	v_add3_u32 v26, v26, v71, s22
	v_add3_u32 v27, v27, v72, s22
	v_add3_u32 v28, v28, v73, s22
	v_add3_u32 v29, v29, v74, s22
	v_add3_u32 v30, v30, v75, s22
	v_add3_u32 v31, v31, v76, s22
	v_lshrrev_b32_e32 v0, 16, v0
	v_and_or_b32 v0, v1, s23, v0
	v_lshrrev_b32_e32 v2, 16, v2
	v_and_or_b32 v1, v3, s23, v2
	v_lshrrev_b32_e32 v4, 16, v4
	v_and_or_b32 v2, v5, s23, v4
	v_lshrrev_b32_e32 v6, 16, v6
	v_and_or_b32 v3, v7, s23, v6
	v_lshrrev_b32_e32 v8, 16, v8
	v_and_or_b32 v8, v9, s23, v8
	v_lshrrev_b32_e32 v10, 16, v10
	v_and_or_b32 v9, v11, s23, v10
	v_lshrrev_b32_e32 v12, 16, v12
	v_and_or_b32 v10, v13, s23, v12
	v_lshrrev_b32_e32 v14, 16, v14
	v_and_or_b32 v11, v15, s23, v14
	v_lshrrev_b32_e32 v16, 16, v16
	v_and_or_b32 v16, v17, s23, v16
	v_lshrrev_b32_e32 v18, 16, v18
	v_and_or_b32 v17, v19, s23, v18
	v_lshrrev_b32_e32 v20, 16, v20
	v_and_or_b32 v18, v21, s23, v20
	v_lshrrev_b32_e32 v22, 16, v22
	v_and_or_b32 v19, v23, s23, v22
	v_lshrrev_b32_e32 v24, 16, v24
	v_and_or_b32 v24, v25, s23, v24
	v_lshrrev_b32_e32 v26, 16, v26
	v_and_or_b32 v25, v27, s23, v26
	v_lshrrev_b32_e32 v28, 16, v28
	v_and_or_b32 v26, v29, s23, v28
	v_lshrrev_b32_e32 v30, 16, v30
	v_and_or_b32 v27, v31, s23, v30
	global_store_dwordx4 v66, v[0:3], s[14:15]
	s_add_u32 s14, s14, 0x4000
	s_addc_u32 s15, s15, 0
	global_store_dwordx4 v66, v[8:11], s[14:15]
	s_add_u32 s14, s14, 0x4000
	s_addc_u32 s15, s15, 0
	global_store_dwordx4 v66, v[16:19], s[14:15]
	s_add_u32 s14, s14, 0x4000
	s_addc_u32 s15, s15, 0
	global_store_dwordx4 v66, v[24:27], s[14:15]
	s_cmpk_gt_u32 s4, 0x5ff
	s_cbranch_scc1 .Lp4_done
; #define LAS __attribute__((address_space(3)))
; __device__ __forceinline__ unsigned pk2(float lo, float hi) { return f2bf(lo) | (f2bf(hi) << 16); }
; __device__ __forceinline__ void p0_transpose_kn(const float* W, int K, int N, bf16_t* WT, int row_off, LAS float* scr, int kb, int nb, int lane) {
;     ...
;     for (int i = 0; i < 32; ++i) wv[i] = W[(size_t)(k0 + 2 * i + (lane >> 5)) * N + n0 + (lane & 31)];
; #pragma unroll
;     for (int i = 0; i < 32; ++i) scr[(2 * i + (lane >> 5)) * 33 + (lane & 31)] = wv[i];
;     asm volatile("s_waitcnt lgkmcnt(0)" ::: "memory");
;     const int c = lane & 7;
; #pragma unroll
;     for (int j = 0; j < 4; ++j) { const int n = (lane >> 3) + 8 * j; const LAS float* s = scr + (8 * c) * 33 + n;
;         u32x4 o; o.x = pk2(s[0 * 33], s[1 * 33]); o.y = pk2(s[2 * 33], s[3 * 33]); o.z = pk2(s[4 * 33], s[5 * 33]); o.w = pk2(s[6 * 33], s[7 * 33]);
;         *(u32x4*)(WT + (size_t)(row_off + n0 + n) * K + k0 + 8 * c) = o; }
;     asm volatile("s_waitcnt lgkmcnt(0)" ::: "memory");
; __global__ void __launch_bounds__(512, 2) mk_fwd(Args args) {
;     ...
;             __syncthreads();
;         }
;         if (scan_in_p2) grp_wait(cntS + 64 * (vb >> 5), 32u);
	s_waitcnt vmcnt(4)
	ds_write_b32 v67, v32
	ds_write_b32 v67, v33 offset:264
	ds_write_b32 v67, v34 offset:528
	ds_write_b32 v67, v35 offset:792
	ds_write_b32 v67, v36 offset:1056
	ds_write_b32 v67, v37 offset:1320
	ds_write_b32 v67, v38 offset:1584
	ds_write_b32 v67, v39 offset:1848
	ds_write_b32 v67, v40 offset:2112
	ds_write_b32 v67, v41 offset:2376
	ds_write_b32 v67, v42 offset:2640
	ds_write_b32 v67, v43 offset:2904
	ds_write_b32 v67, v44 offset:3168
	ds_write_b32 v67, v45 offset:3432
	ds_write_b32 v67, v46 offset:3696
	ds_write_b32 v67, v47 offset:3960
	ds_write_b32 v67, v48 offset:4224
	ds_write_b32 v67, v49 offset:4488
	ds_write_b32 v67, v50 offset:4752
	ds_write_b32 v67, v51 offset:5016
	ds_write_b32 v67, v52 offset:5280
	ds_write_b32 v67, v53 offset:5544
	ds_write_b32 v67, v54 offset:5808
	ds_write_b32 v67, v55 offset:6072
	ds_write_b32 v67, v56 offset:6336
	ds_write_b32 v67, v57 offset:6600
	ds_write_b32 v67, v58 offset:6864
	ds_write_b32 v67, v59 offset:7128
	ds_write_b32 v67, v60 offset:7392
	ds_write_b32 v67, v61 offset:7656
	ds_write_b32 v67, v62 offset:7920
	ds_write_b32 v67, v63 offset:8184
	s_waitcnt lgkmcnt(0)
	ds_read2_b32 v[32:33], v68 offset1:33
	ds_read2_b32 v[34:35], v68 offset0:66 offset1:99
	ds_read2_b32 v[36:37], v68 offset0:132 offset1:165
	ds_read2_b32 v[38:39], v68 offset0:198 offset1:231
	ds_read2_b32 v[40:41], v68 offset0:8 offset1:41
	ds_read2_b32 v[42:43], v68 offset0:74 offset1:107
	ds_read2_b32 v[44:45], v68 offset0:140 offset1:173
	ds_read2_b32 v[46:47], v68 offset0:206 offset1:239
	ds_read2_b32 v[48:49], v68 offset0:16 offset1:49
	ds_read2_b32 v[50:51], v68 offset0:82 offset1:115
	ds_read2_b32 v[52:53], v68 offset0:148 offset1:181
	ds_read2_b32 v[54:55], v68 offset0:214 offset1:247
	ds_read2_b32 v[56:57], v68 offset0:24 offset1:57
	ds_read2_b32 v[58:59], v68 offset0:90 offset1:123
	ds_read2_b32 v[60:61], v68 offset0:156 offset1:189
	ds_read2_b32 v[62:63], v68 offset0:222 offset1:255
	s_waitcnt lgkmcnt(0)
	v_bfe_u32 v69, v32, 16, 1
	v_bfe_u32 v70, v33, 16, 1
	v_bfe_u32 v71, v34, 16, 1
	v_bfe_u32 v72, v35, 16, 1
	v_bfe_u32 v73, v36, 16, 1
	v_bfe_u32 v74, v37, 16, 1
	v_bfe_u32 v75, v38, 16, 1
	v_bfe_u32 v76, v39, 16, 1
	v_add3_u32 v32, v32, v69, s22
	v_add3_u32 v33, v33, v70, s22
	v_add3_u32 v34, v34, v71, s22
	v_add3_u32 v35, v35, v72, s22
	v_add3_u32 v36, v36, v73, s22
	v_add3_u32 v37, v37, v74, s22
	v_add3_u32 v38, v38, v75, s22
	v_add3_u32 v39, v39, v76, s22
	v_bfe_u32 v69, v40, 16, 1
	v_bfe_u32 v70, v41, 16, 1
	v_bfe_u32 v71, v42, 16, 1
	v_bfe_u32 v72, v43, 16, 1
	v_bfe_u32 v73, v44, 16, 1
	v_bfe_u32 v74, v45, 16, 1
	v_bfe_u32 v75, v46, 16, 1
	v_bfe_u32 v76, v47, 16, 1
	v_add3_u32 v40, v40, v69, s22
	v_add3_u32 v41, v41, v70, s22
	v_add3_u32 v42, v42, v71, s22
	v_add3_u32 v43, v43, v72, s22
	v_add3_u32 v44, v44, v73, s22
	v_add3_u32 v45, v45, v74, s22
	v_add3_u32 v46, v46, v75, s22
	v_add3_u32 v47, v47, v76, s22
	v_bfe_u32 v69, v48, 16, 1
	v_bfe_u32 v70, v49, 16, 1
	v_bfe_u32 v71, v50, 16, 1
	v_bfe_u32 v72, v51, 16, 1
	v_bfe_u32 v73, v52, 16, 1
	v_bfe_u32 v74, v53, 16, 1
	v_bfe_u32 v75, v54, 16, 1
	v_bfe_u32 v76, v55, 16, 1
	v_add3_u32 v48, v48, v69, s22
	v_add3_u32 v49, v49, v70, s22
	v_add3_u32 v50, v50, v71, s22
	v_add3_u32 v51, v51, v72, s22
	v_add3_u32 v52, v52, v73, s22
	v_add3_u32 v53, v53, v74, s22
	v_add3_u32 v54, v54, v75, s22
	v_add3_u32 v55, v55, v76, s22
	v_bfe_u32 v69, v56, 16, 1
	v_bfe_u32 v70, v57, 16, 1
	v_bfe_u32 v71, v58, 16, 1
	v_bfe_u32 v72, v59, 16, 1
	v_bfe_u32 v73, v60, 16, 1
	v_bfe_u32 v74, v61, 16, 1
	v_bfe_u32 v75, v62, 16, 1
	v_bfe_u32 v76, v63, 16, 1
	v_add3_u32 v56, v56, v69, s22
	v_add3_u32 v57, v57, v70, s22
	v_add3_u32 v58, v58, v71, s22
	v_add3_u32 v59, v59, v72, s22
	v_add3_u32 v60, v60, v73, s22
	v_add3_u32 v61, v61, v74, s22
	v_add3_u32 v62, v62, v75, s22
	v_add3_u32 v63, v63, v76, s22
	v_lshrrev_b32_e32 v32, 16, v32
	v_and_or_b32 v32, v33, s23, v32
	v_lshrrev_b32_e32 v34, 16, v34
	v_and_or_b32 v33, v35, s23, v34
	v_lshrrev_b32_e32 v36, 16, v36
	v_and_or_b32 v34, v37, s23, v36
	v_lshrrev_b32_e32 v38, 16, v38
	v_and_or_b32 v35, v39, s23, v38
	v_lshrrev_b32_e32 v40, 16, v40
	v_and_or_b32 v40, v41, s23, v40
	v_lshrrev_b32_e32 v42, 16, v42
	v_and_or_b32 v41, v43, s23, v42
	v_lshrrev_b32_e32 v44, 16, v44
	v_and_or_b32 v42, v45, s23, v44
	v_lshrrev_b32_e32 v46, 16, v46
	v_and_or_b32 v43, v47, s23, v46
	v_lshrrev_b32_e32 v48, 16, v48
	v_and_or_b32 v48, v49, s23, v48
	v_lshrrev_b32_e32 v50, 16, v50
	v_and_or_b32 v49, v51, s23, v50
	v_lshrrev_b32_e32 v52, 16, v52
	v_and_or_b32 v50, v53, s23, v52
	v_lshrrev_b32_e32 v54, 16, v54
	v_and_or_b32 v51, v55, s23, v54
	v_lshrrev_b32_e32 v56, 16, v56
	v_and_or_b32 v56, v57, s23, v56
	v_lshrrev_b32_e32 v58, 16, v58
	v_and_or_b32 v57, v59, s23, v58
	v_lshrrev_b32_e32 v60, 16, v60
	v_and_or_b32 v58, v61, s23, v60
	v_lshrrev_b32_e32 v62, 16, v62
	v_and_or_b32 v59, v63, s23, v62
	global_store_dwordx4 v66, v[32:35], s[20:21]
	s_add_u32 s20, s20, 0x4000
	s_addc_u32 s21, s21, 0
	global_store_dwordx4 v66, v[40:43], s[20:21]
	s_add_u32 s20, s20, 0x4000
	s_addc_u32 s21, s21, 0
	global_store_dwordx4 v66, v[48:51], s[20:21]
	s_add_u32 s20, s20, 0x4000
	s_addc_u32 s21, s21, 0
	global_store_dwordx4 v66, v[56:59], s[20:21]
.Lp4_done:
.LBB0_415:
	s_and_b64 vcc, exec, s[80:81]
	s_waitcnt vmcnt(0)
	s_barrier
	s_cbranch_vccz .LBB0_427
	s_and_saveexec_b64 s[4:5], s[92:93]
	s_cbranch_execz .LBB0_426
	s_lshl_b32 s1, s49, 1
	s_and_b32 s6, s1, 0xffffffc0
	s_ashr_i32 s7, s6, 31
	s_lshl_b64 s[6:7], s[6:7], 2
	s_add_u32 s6, s58, s6
	s_addc_u32 s7, s59, s7
	s_mov_b32 s1, 0x400001
	v_mov_b32_e32 v0, 0
	s_branch .LBB0_419
